# combo7 + mixer-A tile loop: next tile's K/V global loads issued right after the staging stores instead of after the row-sum adds, the barrier and the latch
# baseline (speedup 1.0000x reference)
; #define LAS __attribute__((address_space(3)))
; __device__ __forceinline__ unsigned pk_bf16(float lo, float hi) { return pg8::cvt_pk_bf16(lo, hi); }
; template <int MODE> ...
;     ...
;         if (it + 1 < nT) { kreg = *(const u32x4*)(kg + (size_t)((T + 1) * 64) * INW); vreg = *(const u32x4*)(vg + (T + 1) * 64); }
;     ...
;             for (int i = 0; i < 16; ++i) { s0[i] = __builtin_amdgcn_exp2f(s0[i] - mnew); s1[i] = __builtin_amdgcn_exp2f(s1[i] - mnew); ps += s0[i] + s1[i]; }
;             l = l * alpha + ps;
; #pragma unroll
;             for (int i = 0; i < 16; ++i) { o0[i] *= alpha; o1[i] *= alpha; }
;             u32x4 pw[4];
; #pragma unroll
;             for (int q = 0; q < 4; ++q) { pw[0][q] = pk_bf16(s0[2 * q], s0[2 * q + 1]); pw[1][q] = pk_bf16(s0[8 + 2 * q], s0[8 + 2 * q + 1]);
;                                           pw[2][q] = pk_bf16(s1[2 * q], s1[2 * q + 1]); pw[3][q] = pk_bf16(s1[8 + 2 * q], s1[8 + 2 * q + 1]); }
;             const LAS unsigned char* vb = lds + ATT_V + buf * ATT_TILE + r * KP + 16 * h;
; #pragma unroll
;             for (int ks = 0; ks < 4; ++ks) {
;                 const bf16x8 a0 = *(const LAS bf16x8*)(vb + 32 * ks);
;                 const bf16x8 a1 = *(const LAS bf16x8*)(vb + 32 * KP + 32 * ks);
;                 const bf16x8 pf = __builtin_bit_cast(bf16x8, pw[ks]);
;                 o0 = __builtin_amdgcn_mfma_f32_32x32x16_bf16(a0, pf, o0, 0, 0, 0);
;                 o1 = __builtin_amdgcn_mfma_f32_32x32x16_bf16(a1, pf, o1, 0, 0, 0);
;             }
;         }
;         if (it + 1 < nT) { *(LAS u32x4*)(lds + ATT_K + (buf ^ 1) * ATT_TILE + sdst) = kreg; *(LAS u32x4*)(lds + ATT_V + (buf ^ 1) * ATT_TILE + sdst) = vreg; }
;         __syncthreads();
.Lal_a2:
	s_mov_b64 exec, -1
	ds_read_b128 v[188:191], v211 offset:23072
	v_sub_f32_e32 v54, v54, v34
	v_sub_f32_e32 v55, v55, v34
	v_sub_f32_e32 v56, v56, v34
	v_sub_f32_e32 v58, v58, v34
	s_waitcnt lgkmcnt(2)
	v_mfma_f32_32x32x16_bf16 v[16:31], v[192:195], v[60:63], v[16:31]
	v_sub_f32_e32 v61, v215, v34
	v_exp_f32_e32 v54, v54
	v_exp_f32_e32 v55, v55
	v_exp_f32_e32 v56, v56
	v_exp_f32_e32 v57, v57
	v_exp_f32_e32 v58, v58
	v_exp_f32_e32 v59, v59
	v_exp_f32_e32 v60, v197
	v_exp_f32_e32 v61, v61
	v_cvt_pk_bf16_f32 v192, v54, v55
	v_cvt_pk_bf16_f32 v193, v56, v57
	v_cvt_pk_bf16_f32 v194, v58, v59
	v_cvt_pk_bf16_f32 v195, v60, v61
	v_sub_f32_e32 v41, v205, v34
	v_sub_f32_e32 v45, v207, v34
	s_waitcnt lgkmcnt(1)
	v_mfma_f32_32x32x16_bf16 v[0:15], v[200:203], v[192:195], v[0:15]
	ds_read_b128 v[200:203], v211 offset:18496
	v_sub_f32_e32 v53, v213, v34
	v_exp_f32_e32 v38, v38
	v_exp_f32_e32 v41, v41
	v_exp_f32_e32 v43, v43
	v_exp_f32_e32 v45, v45
	v_exp_f32_e32 v47, v47
	s_waitcnt lgkmcnt(1)
	v_mfma_f32_32x32x16_bf16 v[16:31], v[188:191], v[192:195], v[16:31]
	v_exp_f32_e32 v49, v49
	v_exp_f32_e32 v51, v51
	v_exp_f32_e32 v53, v53
	v_sub_f32_e32 v62, v196, v34
	ds_read_b128 v[194:197], v211 offset:23104
	ds_read_b128 v[204:207], v211 offset:18528
	v_cvt_pk_bf16_f32 v190, v38, v41
	v_cvt_pk_bf16_f32 v191, v43, v45
	v_cvt_pk_bf16_f32 v192, v47, v49
	v_cvt_pk_bf16_f32 v193, v51, v53
	v_sub_f32_e32 v37, v37, v34
	v_sub_f32_e32 v63, v198, v34
	s_waitcnt lgkmcnt(2)
	v_mfma_f32_32x32x16_bf16 v[0:15], v[200:203], v[190:193], v[0:15]
	ds_read_b128 v[200:203], v211 offset:23136
	v_sub_f32_e32 v39, v39, v34
	v_sub_f32_e32 v188, v208, v34
	v_sub_f32_e32 v35, v35, v34
	v_sub_f32_e32 v189, v210, v34
	v_sub_f32_e32 v33, v33, v34
	v_exp_f32_e32 v62, v62
	s_waitcnt lgkmcnt(2)
	v_mfma_f32_32x32x16_bf16 v[16:31], v[194:197], v[190:193], v[16:31]
	v_exp_f32_e32 v37, v37
	v_exp_f32_e32 v63, v63
	v_exp_f32_e32 v39, v39
	v_exp_f32_e32 v188, v188
	v_exp_f32_e32 v35, v35
	v_exp_f32_e32 v189, v189
	v_exp_f32_e32 v33, v33
	v_cvt_pk_bf16_f32 v190, v62, v37
	v_cvt_pk_bf16_f32 v191, v63, v39
	v_cvt_pk_bf16_f32 v192, v188, v35
	v_cvt_pk_bf16_f32 v193, v189, v33
	s_waitcnt lgkmcnt(1)
	s_nop 0
	v_mfma_f32_32x32x16_bf16 v[0:15], v[204:207], v[190:193], v[0:15]
	s_waitcnt lgkmcnt(0)
	v_mfma_f32_32x32x16_bf16 v[16:31], v[200:203], v[190:193], v[16:31]
	s_cbranch_vccnz .LBB0_296
	s_xor_b32 s4, s4, 1
	s_mulk_i32 s4, 0x2400
	v_add_u32_e32 v190, s4, v183
	s_waitcnt vmcnt(1)
	ds_write_b128 v190, v[80:83]
	s_waitcnt vmcnt(0)
	ds_write_b128 v190, v[84:87] offset:18432
	s_add_i32 s4, s11, 1
	s_cmp_ge_i32 s4, s26
	s_cbranch_scc1 .Lpfa_skip
	s_add_i32 s4, s92, 0x80
	v_mad_i64_i32 v[204:205], s[4:5], s4, v223, v[160:161]
	s_add_i32 s100, s92, 64
	s_ashr_i32 s101, s100, 31
	v_lshl_add_u64 v[206:207], s[100:101], 1, v[158:159]
	global_load_dwordx4 v[80:83], v[204:205], off offset:1024
	global_load_dwordx4 v[84:87], v[206:207], off offset:128
.Lpfa_skip:
.LBB0_296:
	v_add_f32_e32 v36, v36, v38
	v_add_f32_e32 v38, v40, v41
	v_add_f32_e32 v36, 0, v36
	v_add_f32_e32 v40, v42, v43
	v_add_f32_e32 v36, v38, v36
	v_add_f32_e32 v41, v44, v45
	v_add_f32_e32 v36, v40, v36
	v_add_f32_e32 v42, v46, v47
	v_add_f32_e32 v36, v41, v36
	v_add_f32_e32 v43, v48, v49
	v_add_f32_e32 v36, v42, v36
	v_add_f32_e32 v44, v50, v51
	v_add_f32_e32 v36, v43, v36
	v_add_f32_e32 v45, v52, v53
	v_add_f32_e32 v36, v44, v36
	v_add_f32_e32 v46, v54, v62
	v_add_f32_e32 v36, v45, v36
	v_add_f32_e32 v37, v55, v37
	v_add_f32_e32 v36, v46, v36
	v_add_f32_e32 v47, v56, v63
	v_add_f32_e32 v36, v37, v36
	v_add_f32_e32 v39, v57, v39
	v_add_f32_e32 v36, v47, v36
	v_add_f32_e32 v48, v58, v188
	v_add_f32_e32 v36, v39, v36
	v_add_f32_e32 v35, v59, v35
	v_add_f32_e32 v36, v48, v36
	v_add_f32_e32 v49, v60, v189
	v_add_f32_e32 v35, v35, v36
	v_add_f32_e32 v33, v61, v33
	v_add_f32_e32 v35, v49, v35
	v_add_f32_e32 v33, v33, v35
	s_add_i32 s11, s11, 1
	s_add_i32 s92, s92, 64
	v_fmac_f32_e32 v33, v184, v32
	s_cmp_eq_u32 s27, s11
	v_add_u32_e32 v187, 0x100, v187
	s_waitcnt lgkmcnt(0)
	s_barrier
	s_cbranch_scc1 .LBB0_299
	v_mov_b32_e32 v184, v33
	v_mov_b32_e32 v188, v34
	s_cmp_lt_i32 s11, s26
	s_cselect_b64 s[20:21], -1, 0
	s_cmp_ge_i32 s11, s26
	s_branch .LBB0_294
